# MIX-2 two work queues: long items (delta_seq chains, s5_prompt scans) only handed to blocks < 256 (one per CU), lru_prompt right after its producers
# speedup vs baseline: 1.0427x; 1.0016x over previous
.LBB0_524:
	s_or_b64 exec, exec, s[2:3]
	s_barrier
	v_readlane_b32 s4, v255, 14
	s_nop 1
	s_lshr_b32 s4, s4, 8
	s_min_u32 s4, s4, 1
	s_nop 0
	v_writelane_b32 v255, s4, 41
	s_branch .LBB0_529

.LBB0_529:
	s_setprio 0
	s_barrier
	s_mov_b64 s[2:3], exec
	v_readlane_b32 s4, v253, 30
	v_readlane_b32 s5, v253, 31
	s_and_b64 s[4:5], s[2:3], s[4:5]
	s_mov_b64 exec, s[4:5]
	s_cbranch_execz .LBB0_533
	s_mov_b64 s[8:9], exec
	s_waitcnt vmcnt(0)
	v_mbcnt_lo_u32_b32 v0, s8, 0
	v_mbcnt_hi_u32_b32 v0, s9, v0
	v_cmp_eq_u32_e32 vcc, 0, v0
	s_and_saveexec_b64 s[4:5], vcc
	s_cbranch_execz .LBB0_532
	s_bcnt1_i32_b64 s8, s[8:9]
	v_mov_b32_e32 v1, s8
	v_readlane_b32 s8, v255, 28
	v_readlane_b32 s9, v255, 29
	v_readlane_b32 s10, v255, 41
	s_nop 4
	s_cmp_eq_u32 s10, 0
	s_cbranch_scc0 .Ltq_short
	s_add_u32 s8, s8, 76
	s_addc_u32 s9, s9, 0
.Ltq_short:
	s_nop 4
	global_atomic_add v1, v201, v1, s[8:9] offset:4 sc0

.LBB0_533:
	s_or_b64 exec, exec, s[2:3]
	s_waitcnt lgkmcnt(0)
	s_barrier
	s_waitcnt vmcnt(0)
	ds_read_b32 v0, v201 offset:64512
	s_movk_i32 s2, 0xc73
	v_readlane_b32 s10, v255, 41
	s_waitcnt lgkmcnt(0)
	s_cmp_eq_u32 s10, 0
	s_cbranch_scc0 .Ltq_fromshort
	v_readfirstlane_b32 s21, v0
	s_nop 0
	s_cmp_lt_u32 s21, 160
	s_cbranch_scc1 .Ltq_have
	s_mov_b32 s10, 1
	s_nop 0
	v_writelane_b32 v255, s10, 41
	s_mov_b64 s[2:3], 0
	s_branch .LBB0_528
.Ltq_fromshort:
	v_add_u32_e32 v0, 0xa0, v0
	s_nop 0
	v_cmp_lt_i32_e32 vcc, s2, v0
	v_readfirstlane_b32 s21, v0
	s_mov_b64 s[2:3], -1
	s_cbranch_vccnz .LBB0_528
.Ltq_have:
	s_cmp_lt_u32 s21, 32
	s_cbranch_scc1 .Lmx_go2
	s_cmp_lt_u32 s21, 160
	s_cbranch_scc0 .Lmx_a
	s_sub_u32 s31, s21, 32
	s_mov_b32 s101, 1
	s_branch .Lmx_disp1
